# stack ST2: as ST1 plus first-iteration vmcnt skip in the FF-in K-loops too
# speedup vs baseline: 1.0049x; 1.0049x over previous
; #define PG8_STAGE(bufoff, gbase, voff) do { _Pragma("unroll") for (int _i = 0; _i < 2; ++_i) \
;         __builtin_amdgcn_global_load_lds((const unsigned*)((const char*)(gbase) + (voff)[_i]), (PG8_LAS unsigned*)(lds + (bufoff) + ldsw + _i * 8192), 16, 0, 0); } while (0)
; #define PG8_LDA(dst, b, h) do { _Pragma("unroll") for (int m = 0; m < 4; ++m) _Pragma("unroll") for (int k = 0; k < 2; ++k) dst[m][k] = *(const PG8_LAS bf16x8*)(lds + PG8_SA(b, h) + aoff + m * 2048 + k * 1024); } while (0)
; #define PG8_LDB(dst, b, h) do { _Pragma("unroll") for (int n = 0; n < 2; ++n) _Pragma("unroll") for (int k = 0; k < 2; ++k) dst[n][k] = *(const PG8_LAS bf16x8*)(lds + PG8_SB(b, h) + boff + n * 2048 + k * 1024); } while (0)
; #define PG8_MMA(ai, bj, At, Bt) do { __builtin_amdgcn_s_setprio(1); _Pragma("unroll") for (int m = 0; m < 4; ++m) _Pragma("unroll") for (int n = 0; n < 2; ++n) _Pragma("unroll") for (int k = 0; k < 2; ++k) \
;         acc[ai][bj][m][n] = __builtin_amdgcn_mfma_f32_16x16x32_bf16(Bt[n][k], At[m][k], acc[ai][bj][m][n], 0, 0, 0); __builtin_amdgcn_s_setprio(0); } while (0)
; #define PG8_WAIT_V(n) asm volatile("s_waitcnt vmcnt(" #n ")" ::: "memory")
; #define PG8_WAIT_L(n) do { asm volatile("s_waitcnt lgkmcnt(" #n ")" ::: "memory"); __builtin_amdgcn_s_waitcnt(0xC07F); } while (0)
; #define PG8_BAR __builtin_amdgcn_s_barrier()
; #define PG8_SCHED __builtin_amdgcn_sched_barrier(0)
; template <class Epi, class Sched, bool SEG3 = false>
; __device__ __forceinline__ void gemm_phase(PG8_LAS unsigned char* lds, const Gemm g, const Sched& S, const Epi& E) {
;     ...
;             PG8_LDB(B0, 0, 0); PG8_LDB(B1, 0, 1); PG8_SCHED; PG8_LDA(At, 0, 0); PG8_STAGE(PG8_SA(1, 1), a1 + hsA, voffA);
;             PG8_WAIT_V(8); PG8_WAIT_L(0); PG8_BAR; if (cur.half != 1) { PG8_MMA(0, 0, At, B0); PG8_MMA(0, 1, At, B1); } PG8_BAR; PG8_SCHED;
.LBB0_435:
	ds_read_b128 v[146:149], v221
	ds_read_b128 v[150:153], v221 offset:1024
	ds_read_b128 v[154:157], v221 offset:2048
	ds_read_b128 v[158:161], v221 offset:3072
	ds_read_b128 v[2:5], v222
	ds_read_b128 v[6:9], v222 offset:1024
	ds_read_b128 v[98:101], v222 offset:2048
	ds_read_b128 v[102:105], v222 offset:3072
	v_lshl_add_u64 v[210:211], s[38:39], 0, v[204:205]
	s_add_i32 m0, s50, 0xc000
	ds_read_b128 v[186:189], v223
	ds_read_b128 v[190:193], v223 offset:1024
	ds_read_b128 v[178:181], v223 offset:2048
	ds_read_b128 v[182:185], v223 offset:3072
	ds_read_b128 v[170:173], v223 offset:4096
	ds_read_b128 v[174:177], v223 offset:5120
	ds_read_b128 v[162:165], v223 offset:6144
	ds_read_b128 v[166:169], v223 offset:7168
	global_load_lds_dwordx4 v[210:211], off
	v_lshl_add_u64 v[210:211], s[38:39], 0, v[206:207]
	s_add_i32 m0, s50, 0xe000
	v_cmp_ne_u32_e64 s[4:5], 1, v226
	global_load_lds_dwordx4 v[210:211], off
	s_cmp_lg_u32 s98, 0
	s_cbranch_scc1 .Lfi_a_0
	s_waitcnt vmcnt(8)
.Lfi_a_0:
	s_andn2_b64 vcc, exec, s[34:35]
	s_waitcnt lgkmcnt(0)
	s_barrier
	s_cbranch_vccnz .LBB0_437
	s_setprio 1
	v_mfma_f32_16x16x32_bf16 v[138:141], v[146:149], v[186:189], v[138:141]
	v_mfma_f32_16x16x32_bf16 v[130:133], v[154:157], v[186:189], v[130:133]
	v_mfma_f32_16x16x32_bf16 v[122:125], v[146:149], v[178:181], v[122:125]
	v_mfma_f32_16x16x32_bf16 v[114:117], v[154:157], v[178:181], v[114:117]
	v_mfma_f32_16x16x32_bf16 v[106:109], v[146:149], v[170:173], v[106:109]
	v_mfma_f32_16x16x32_bf16 v[10:13], v[154:157], v[170:173], v[10:13]
	v_mfma_f32_16x16x32_bf16 v[90:93], v[146:149], v[162:165], v[90:93]
	v_mfma_f32_16x16x32_bf16 v[82:85], v[154:157], v[162:165], v[82:85]
	v_mfma_f32_16x16x32_bf16 v[138:141], v[150:153], v[190:193], v[138:141]
	v_mfma_f32_16x16x32_bf16 v[130:133], v[158:161], v[190:193], v[130:133]
	v_mfma_f32_16x16x32_bf16 v[122:125], v[150:153], v[182:185], v[122:125]
	v_mfma_f32_16x16x32_bf16 v[114:117], v[158:161], v[182:185], v[114:117]
	v_mfma_f32_16x16x32_bf16 v[106:109], v[150:153], v[174:177], v[106:109]
	v_mfma_f32_16x16x32_bf16 v[10:13], v[158:161], v[174:177], v[10:13]
	v_mfma_f32_16x16x32_bf16 v[90:93], v[150:153], v[166:169], v[90:93]
	v_mfma_f32_16x16x32_bf16 v[82:85], v[158:161], v[166:169], v[82:85]
	s_setprio 0
	s_setprio 1
	v_mfma_f32_16x16x32_bf16 v[142:145], v[2:5], v[186:189], v[142:145]
	v_mfma_f32_16x16x32_bf16 v[134:137], v[98:101], v[186:189], v[134:137]
	v_mfma_f32_16x16x32_bf16 v[126:129], v[2:5], v[178:181], v[126:129]
	v_mfma_f32_16x16x32_bf16 v[118:121], v[98:101], v[178:181], v[118:121]
	v_mfma_f32_16x16x32_bf16 v[110:113], v[2:5], v[170:173], v[110:113]
	v_mfma_f32_16x16x32_bf16 v[14:17], v[98:101], v[170:173], v[14:17]
	v_mfma_f32_16x16x32_bf16 v[94:97], v[2:5], v[162:165], v[94:97]
	v_mfma_f32_16x16x32_bf16 v[86:89], v[98:101], v[162:165], v[86:89]
	v_mfma_f32_16x16x32_bf16 v[142:145], v[6:9], v[190:193], v[142:145]
	v_mfma_f32_16x16x32_bf16 v[134:137], v[102:105], v[190:193], v[134:137]
	v_mfma_f32_16x16x32_bf16 v[126:129], v[6:9], v[182:185], v[126:129]
	v_mfma_f32_16x16x32_bf16 v[118:121], v[102:105], v[182:185], v[118:121]
	v_mfma_f32_16x16x32_bf16 v[110:113], v[6:9], v[174:177], v[110:113]
	v_mfma_f32_16x16x32_bf16 v[14:17], v[102:105], v[174:177], v[14:17]
	v_mfma_f32_16x16x32_bf16 v[94:97], v[6:9], v[166:169], v[94:97]
	v_mfma_f32_16x16x32_bf16 v[86:89], v[102:105], v[166:169], v[86:89]
	s_setprio 0
; #define PG8_STAGE(bufoff, gbase, voff) do { _Pragma("unroll") for (int _i = 0; _i < 2; ++_i) \
;         __builtin_amdgcn_global_load_lds((const unsigned*)((const char*)(gbase) + (voff)[_i]), (PG8_LAS unsigned*)(lds + (bufoff) + ldsw + _i * 8192), 16, 0, 0); } while (0)
; #define PG8_LDA(dst, b, h) do { _Pragma("unroll") for (int m = 0; m < 4; ++m) _Pragma("unroll") for (int k = 0; k < 2; ++k) dst[m][k] = *(const PG8_LAS bf16x8*)(lds + PG8_SA(b, h) + aoff + m * 2048 + k * 1024); } while (0)
; #define PG8_MMA(ai, bj, At, Bt) do { __builtin_amdgcn_s_setprio(1); _Pragma("unroll") for (int m = 0; m < 4; ++m) _Pragma("unroll") for (int n = 0; n < 2; ++n) _Pragma("unroll") for (int k = 0; k < 2; ++k) \
;         acc[ai][bj][m][n] = __builtin_amdgcn_mfma_f32_16x16x32_bf16(Bt[n][k], At[m][k], acc[ai][bj][m][n], 0, 0, 0); __builtin_amdgcn_s_setprio(0); } while (0)
; #define PG8_WAIT_V(n) asm volatile("s_waitcnt vmcnt(" #n ")" ::: "memory")
; #define PG8_WAIT_L(n) do { asm volatile("s_waitcnt lgkmcnt(" #n ")" ::: "memory"); __builtin_amdgcn_s_waitcnt(0xC07F); } while (0)
; #define PG8_BAR __builtin_amdgcn_s_barrier()
; #define PG8_SCHED __builtin_amdgcn_sched_barrier(0)
; template <class Epi, class Sched, bool SEG3 = false>
; __device__ __forceinline__ void gemm_phase(PG8_LAS unsigned char* lds, const Gemm g, const Sched& S, const Epi& E) {
;     ...
;             PG8_LDA(At, 0, 1); PG8_STAGE(PG8_SB(0, 0), b2, voffB); PG8_STAGE(PG8_SB(0, 1), b2 + hsB, voffB); PG8_STAGE(PG8_SA(0, 0), a2, voffA);
;             PG8_WAIT_V(8); PG8_WAIT_L(0); PG8_BAR; if (cur.half != 0) { PG8_MMA(1, 0, At, B0); PG8_MMA(1, 1, At, B1); } PG8_BAR; PG8_SCHED;
.LBB0_437:
	s_add_u32 s6, s38, 0xfffc0080
	s_addc_u32 s7, s39, -1
	s_cmp_eq_u32 s65, s77
	s_cselect_b32 s43, s19, s7
	s_cselect_b32 s42, s21, s6
	s_cselect_b32 s41, s75, s79
	s_cselect_b32 s40, s76, s78
	s_barrier
	s_mov_b32 m0, s29
	v_lshl_add_u64 v[210:211], s[40:41], 0, v[196:197]
	s_add_u32 s6, s40, 0x40000
	ds_read_b128 v[186:189], v223 offset:16384
	ds_read_b128 v[190:193], v223 offset:17408
	ds_read_b128 v[178:181], v223 offset:18432
	ds_read_b128 v[182:185], v223 offset:19456
	ds_read_b128 v[170:173], v223 offset:20480
	ds_read_b128 v[174:177], v223 offset:21504
	ds_read_b128 v[162:165], v223 offset:22528
	ds_read_b128 v[166:169], v223 offset:23552
	global_load_lds_dwordx4 v[210:211], off
	v_lshl_add_u64 v[212:213], s[40:41], 0, v[200:201]
	s_mov_b32 m0, s31
	s_addc_u32 s7, s41, 0
	global_load_lds_dwordx4 v[212:213], off
	v_lshl_add_u64 v[214:215], s[6:7], 0, v[196:197]
	s_mov_b32 m0, s48
	v_lshl_add_u64 v[216:217], s[42:43], 0, v[198:199]
	global_load_lds_dwordx4 v[214:215], off
	v_lshl_add_u64 v[214:215], s[6:7], 0, v[200:201]
	s_mov_b32 m0, s49
	v_cndmask_b32_e64 v227, 0, 1, s[36:37]
	global_load_lds_dwordx4 v[214:215], off
	v_lshl_add_u64 v[214:215], s[42:43], 0, v[194:195]
	s_mov_b32 m0, s50
	v_cmp_ne_u32_e64 s[6:7], 1, v227
	global_load_lds_dwordx4 v[214:215], off
	s_mov_b32 m0, s51
	s_andn2_b64 vcc, exec, s[36:37]
	global_load_lds_dwordx4 v[216:217], off
	s_cmp_lg_u32 s98, 0
	s_cbranch_scc1 .Lfi_b_0
	s_waitcnt vmcnt(8)
.Lfi_b_0:
	s_mov_b32 s98, 0
	s_waitcnt lgkmcnt(0)
	s_barrier
	s_cbranch_vccnz .LBB0_439
	s_setprio 1
	v_mfma_f32_16x16x32_bf16 v[74:77], v[146:149], v[186:189], v[74:77]
	v_mfma_f32_16x16x32_bf16 v[66:69], v[154:157], v[186:189], v[66:69]
	v_mfma_f32_16x16x32_bf16 v[58:61], v[146:149], v[178:181], v[58:61]
	v_mfma_f32_16x16x32_bf16 v[50:53], v[154:157], v[178:181], v[50:53]
	v_mfma_f32_16x16x32_bf16 v[42:45], v[146:149], v[170:173], v[42:45]
	v_mfma_f32_16x16x32_bf16 v[34:37], v[154:157], v[170:173], v[34:37]
	v_mfma_f32_16x16x32_bf16 v[26:29], v[146:149], v[162:165], v[26:29]
	v_mfma_f32_16x16x32_bf16 v[22:25], v[154:157], v[162:165], v[22:25]
	v_mfma_f32_16x16x32_bf16 v[74:77], v[150:153], v[190:193], v[74:77]
	v_mfma_f32_16x16x32_bf16 v[66:69], v[158:161], v[190:193], v[66:69]
	v_mfma_f32_16x16x32_bf16 v[58:61], v[150:153], v[182:185], v[58:61]
	v_mfma_f32_16x16x32_bf16 v[50:53], v[158:161], v[182:185], v[50:53]
	v_mfma_f32_16x16x32_bf16 v[42:45], v[150:153], v[174:177], v[42:45]
	v_mfma_f32_16x16x32_bf16 v[34:37], v[158:161], v[174:177], v[34:37]
	v_mfma_f32_16x16x32_bf16 v[26:29], v[150:153], v[166:169], v[26:29]
	v_mfma_f32_16x16x32_bf16 v[22:25], v[158:161], v[166:169], v[22:25]
	s_setprio 0
	s_setprio 1
	v_mfma_f32_16x16x32_bf16 v[78:81], v[2:5], v[186:189], v[78:81]
	v_mfma_f32_16x16x32_bf16 v[62:65], v[2:5], v[178:181], v[62:65]
	v_mfma_f32_16x16x32_bf16 v[46:49], v[2:5], v[170:173], v[46:49]
	v_mfma_f32_16x16x32_bf16 v[2:5], v[2:5], v[162:165], v[30:33]
	v_mfma_f32_16x16x32_bf16 v[70:73], v[98:101], v[186:189], v[70:73]
	v_mfma_f32_16x16x32_bf16 v[54:57], v[98:101], v[178:181], v[54:57]
	v_mfma_f32_16x16x32_bf16 v[38:41], v[98:101], v[170:173], v[38:41]
	v_mfma_f32_16x16x32_bf16 v[30:33], v[6:9], v[166:169], v[2:5]
	v_mfma_f32_16x16x32_bf16 v[2:5], v[98:101], v[162:165], v[18:21]
	v_mfma_f32_16x16x32_bf16 v[78:81], v[6:9], v[190:193], v[78:81]
	v_mfma_f32_16x16x32_bf16 v[70:73], v[102:105], v[190:193], v[70:73]
	v_mfma_f32_16x16x32_bf16 v[62:65], v[6:9], v[182:185], v[62:65]
	v_mfma_f32_16x16x32_bf16 v[54:57], v[102:105], v[182:185], v[54:57]
	v_mfma_f32_16x16x32_bf16 v[46:49], v[6:9], v[174:177], v[46:49]
	v_mfma_f32_16x16x32_bf16 v[38:41], v[102:105], v[174:177], v[38:41]
	v_mfma_f32_16x16x32_bf16 v[18:21], v[102:105], v[166:169], v[2:5]
	s_setprio 0

;     __device__ __forceinline__ void operator()(AccT acc, const Unit& u, int wr, int wc, int fr, int fq) const {
;         const int col0 = u.pn * HALF + wc * 32 + 8 * fq, tc0 = u.pn * BM + wc * 32 + 8 * fq;
;         const bool uni = u.pm < NPROMPT / BM;
;         f32x4 su[2] = {(f32x4){0.f, 0.f, 0.f, 0.f}, (f32x4){0.f, 0.f, 0.f, 0.f}}, sv[2] = {(f32x4){0.f, 0.f, 0.f, 0.f}, (f32x4){0.f, 0.f, 0.f, 0.f}};
;         if (uni) { const float* sw = SHW + (size_t)(u.pm >> 3) * (2 * DFF) + tc0; su[0] = *(const f32x4*)sw; su[1] = *(const f32x4*)(sw + 4); sv[0] = *(const f32x4*)(sw + HALF); sv[1] = *(const f32x4*)(sw + HALF + 4); }
.LBB0_446:
	s_mov_b32 s98, 1
	v_lshl_or_b32 v146, s28, 8, v220
	s_cmpk_gt_i32 s30, 0x7f
	s_mov_b64 s[6:7], -1
	s_cselect_b64 s[4:5], -1, 0
	s_cmpk_lt_i32 s30, 0x80
	v_ashrrev_i32_e32 v147, 31, v146
	s_cbranch_scc1 .LBB0_448
	s_mov_b64 s[6:7], 0
